# ada GEMV loads issued 16-deep instead of one per vmcnt0; ada blocks skip weight-convert items; ctx in-proj tiles moved to light blocks; on top of inproj pipelined k-loop and SSD DPP edits
# speedup vs baseline: 1.0383x; 1.0383x over previous
.LBB0_25:
	s_cmpk_gt_i32 s72, 0x357
	s_cbranch_scc1 .LBB0_82
	s_waitcnt lgkmcnt(0)
	s_add_u32 s18, s2, 0xd00000
	s_addc_u32 s19, s3, 0
	s_add_u32 s20, s2, 0xa00000
	s_addc_u32 s21, s3, 0
	s_add_u32 s22, s2, 0xe00000
	s_addc_u32 s23, s3, 0
	s_movk_i32 s30, 0x100
	s_movk_i32 s31, 0x90
	s_movk_i32 s34, 0x7fff
	v_mov_b32_e32 v49, 0
	s_movk_i32 s35, 0x400
	s_movk_i32 s36, 0x600
	s_mov_b32 s37, 0xe070381d
	s_movk_i32 s38, 0x49
	s_movk_i32 s39, 0x1220
	s_movk_i32 s40, 0x4880
	s_movk_i32 s41, 0x2000
	s_mov_b64 s[24:25], 0x400
	s_movk_i32 s42, 0x22ff
	s_mov_b32 s43, 0x2aaaaaab
	s_mov_b32 s44, 0x1800000
	s_movk_i32 s45, 0x1800
	s_movk_i32 s46, 0x6000
	s_mov_b32 s47, 0xc000
	s_mov_b32 s48, 0x12000
	s_mov_b32 s49, 0x18000
	s_mov_b32 s50, 0x1e000
	s_mov_b32 s51, 0x24000
	s_mov_b32 s52, 0x2a000
	s_mov_b32 s53, 0x30000
	s_mov_b32 s54, 0x36000
	s_mov_b32 s55, 0x3c000
	s_mov_b32 s56, 0x42000
	s_mov_b32 s57, 0x48000
	s_mov_b32 s58, 0x4e000
	s_mov_b32 s59, 0x54000
	s_mov_b32 s60, 0x5a000
	s_mov_b64 s[26:27], 0xc000
	s_movk_i32 s61, 0x37f
	v_mov_b32_e32 v53, 13
	v_mov_b32_e32 v62, 2
	v_mov_b32_e32 v63, 6
	v_mov_b32_e32 v64, 3
	v_mov_b32_e32 v65, 4
	s_mov_b32 s62, s72
	s_mov_b32 s98, s33
	s_cmpk_lg_i32 s33, 0x100
	s_cbranch_scc1 .Lp0_stride_done
	s_movk_i32 s98, 0xd0
	s_cmp_gt_i32 s72, 47
	s_cbranch_scc1 .Lp0_stride_done
	s_movk_i32 s98, 0x400
.Lp0_stride_done:
	s_branch .LBB0_28
.LBB0_27:
	s_add_i32 s62, s62, s98
	s_cmpk_lt_i32 s62, 0x358
	s_cbranch_scc0 .LBB0_82

.LBB0_75:
	global_load_dword v108, v50, s[12:13]
	global_load_dword v109, v50, s[12:13] offset:1024
	global_load_dword v110, v50, s[12:13] offset:2048
	global_load_dword v111, v50, s[12:13] offset:3072
	v_add_u32_e32 v145, 0x1000, v50
	global_load_dword v112, v145, s[12:13]
	global_load_dword v113, v145, s[12:13] offset:1024
	global_load_dword v114, v145, s[12:13] offset:2048
	global_load_dword v115, v145, s[12:13] offset:3072
	v_add_u32_e32 v146, 0x2000, v50
	global_load_dword v116, v146, s[12:13]
	global_load_dword v117, v146, s[12:13] offset:1024
	global_load_dword v118, v146, s[12:13] offset:2048
	global_load_dword v119, v146, s[12:13] offset:3072
	v_add_u32_e32 v147, 0x3000, v50
	global_load_dword v120, v147, s[12:13]
	global_load_dword v121, v147, s[12:13] offset:1024
	global_load_dword v122, v147, s[12:13] offset:2048
	global_load_dword v123, v147, s[12:13] offset:3072
	v_add_u32_e32 v148, 0x4000, v50
	global_load_dword v124, v148, s[12:13]
	global_load_dword v125, v148, s[12:13] offset:1024
	global_load_dword v126, v148, s[12:13] offset:2048
	global_load_dword v127, v148, s[12:13] offset:3072
	v_add_u32_e32 v149, 0x5000, v50
	global_load_dword v128, v149, s[12:13]
	global_load_dword v129, v149, s[12:13] offset:1024
	global_load_dword v130, v149, s[12:13] offset:2048
	global_load_dword v131, v149, s[12:13] offset:3072
	v_add_u32_e32 v150, 0x6000, v50
	global_load_dword v132, v150, s[12:13]
	global_load_dword v133, v150, s[12:13] offset:1024
	global_load_dword v134, v150, s[12:13] offset:2048
	global_load_dword v135, v150, s[12:13] offset:3072
	v_add_u32_e32 v151, 0x7000, v50
	global_load_dword v136, v151, s[12:13]
	global_load_dword v137, v151, s[12:13] offset:1024
	global_load_dword v138, v151, s[12:13] offset:2048
	global_load_dword v139, v151, s[12:13] offset:3072
	global_load_dword v140, v50, s[4:5]
	global_load_dword v141, v50, s[4:5] offset:1024
	global_load_dword v142, v50, s[4:5] offset:2048
	global_load_dword v143, v50, s[4:5] offset:3072
	s_waitcnt vmcnt(35)
	v_mul_f32_e32 v152, 0xbfb8aa3b, v108
	v_exp_f32_e32 v152, v152
	s_nop 0
	v_add_f32_e32 v152, 1.0, v152
	v_rcp_f32_e32 v152, v152
	s_nop 0
	v_mul_f32_e32 v152, v108, v152
	ds_write_b32 v3, v152
	s_waitcnt vmcnt(34)
	v_mul_f32_e32 v153, 0xbfb8aa3b, v109
	v_exp_f32_e32 v153, v153
	s_nop 0
	v_add_f32_e32 v153, 1.0, v153
	v_rcp_f32_e32 v153, v153
	s_nop 0
	v_mul_f32_e32 v153, v109, v153
	ds_write_b32 v3, v153 offset:1024
	s_waitcnt vmcnt(33)
	v_mul_f32_e32 v152, 0xbfb8aa3b, v110
	v_exp_f32_e32 v152, v152
	s_nop 0
	v_add_f32_e32 v152, 1.0, v152
	v_rcp_f32_e32 v152, v152
	s_nop 0
	v_mul_f32_e32 v152, v110, v152
	ds_write_b32 v3, v152 offset:2048
	s_waitcnt vmcnt(32)
	v_mul_f32_e32 v153, 0xbfb8aa3b, v111
	v_exp_f32_e32 v153, v153
	s_nop 0
	v_add_f32_e32 v153, 1.0, v153
	v_rcp_f32_e32 v153, v153
	s_nop 0
	v_mul_f32_e32 v153, v111, v153
	ds_write_b32 v3, v153 offset:3072
	s_waitcnt vmcnt(31)
	v_mul_f32_e32 v152, 0xbfb8aa3b, v112
	v_exp_f32_e32 v152, v152
	s_nop 0
	v_add_f32_e32 v152, 1.0, v152
	v_rcp_f32_e32 v152, v152
	s_nop 0
	v_mul_f32_e32 v152, v112, v152
	ds_write_b32 v3, v152 offset:4096
	s_waitcnt vmcnt(30)
	v_mul_f32_e32 v153, 0xbfb8aa3b, v113
	v_exp_f32_e32 v153, v153
	s_nop 0
	v_add_f32_e32 v153, 1.0, v153
	v_rcp_f32_e32 v153, v153
	s_nop 0
	v_mul_f32_e32 v153, v113, v153
	ds_write_b32 v3, v153 offset:5120
	s_waitcnt vmcnt(29)
	v_mul_f32_e32 v152, 0xbfb8aa3b, v114
	v_exp_f32_e32 v152, v152
	s_nop 0
	v_add_f32_e32 v152, 1.0, v152
	v_rcp_f32_e32 v152, v152
	s_nop 0
	v_mul_f32_e32 v152, v114, v152
	ds_write_b32 v3, v152 offset:6144
	s_waitcnt vmcnt(28)
	v_mul_f32_e32 v153, 0xbfb8aa3b, v115
	v_exp_f32_e32 v153, v153
	s_nop 0
	v_add_f32_e32 v153, 1.0, v153
	v_rcp_f32_e32 v153, v153
	s_nop 0
	v_mul_f32_e32 v153, v115, v153
	ds_write_b32 v3, v153 offset:7168
	s_waitcnt vmcnt(27)
	v_mul_f32_e32 v152, 0xbfb8aa3b, v116
	v_exp_f32_e32 v152, v152
	s_nop 0
	v_add_f32_e32 v152, 1.0, v152
	v_rcp_f32_e32 v152, v152
	s_nop 0
	v_mul_f32_e32 v152, v116, v152
	ds_write_b32 v3, v152 offset:8192
	s_waitcnt vmcnt(26)
	v_mul_f32_e32 v153, 0xbfb8aa3b, v117
	v_exp_f32_e32 v153, v153
	s_nop 0
	v_add_f32_e32 v153, 1.0, v153
	v_rcp_f32_e32 v153, v153
	s_nop 0
	v_mul_f32_e32 v153, v117, v153
	ds_write_b32 v3, v153 offset:9216
	s_waitcnt vmcnt(25)
	v_mul_f32_e32 v152, 0xbfb8aa3b, v118
	v_exp_f32_e32 v152, v152
	s_nop 0
	v_add_f32_e32 v152, 1.0, v152
	v_rcp_f32_e32 v152, v152
	s_nop 0
	v_mul_f32_e32 v152, v118, v152
	ds_write_b32 v3, v152 offset:10240
	s_waitcnt vmcnt(24)
	v_mul_f32_e32 v153, 0xbfb8aa3b, v119
	v_exp_f32_e32 v153, v153
	s_nop 0
	v_add_f32_e32 v153, 1.0, v153
	v_rcp_f32_e32 v153, v153
	s_nop 0
	v_mul_f32_e32 v153, v119, v153
	ds_write_b32 v3, v153 offset:11264
	s_waitcnt vmcnt(23)
	v_mul_f32_e32 v152, 0xbfb8aa3b, v120
	v_exp_f32_e32 v152, v152
	s_nop 0
	v_add_f32_e32 v152, 1.0, v152
	v_rcp_f32_e32 v152, v152
	s_nop 0
	v_mul_f32_e32 v152, v120, v152
	ds_write_b32 v3, v152 offset:12288
	s_waitcnt vmcnt(22)
	v_mul_f32_e32 v153, 0xbfb8aa3b, v121
	v_exp_f32_e32 v153, v153
	s_nop 0
	v_add_f32_e32 v153, 1.0, v153
	v_rcp_f32_e32 v153, v153
	s_nop 0
	v_mul_f32_e32 v153, v121, v153
	ds_write_b32 v3, v153 offset:13312
	s_waitcnt vmcnt(21)
	v_mul_f32_e32 v152, 0xbfb8aa3b, v122
	v_exp_f32_e32 v152, v152
	s_nop 0
	v_add_f32_e32 v152, 1.0, v152
	v_rcp_f32_e32 v152, v152
	s_nop 0
	v_mul_f32_e32 v152, v122, v152
	ds_write_b32 v3, v152 offset:14336
	s_waitcnt vmcnt(20)
	v_mul_f32_e32 v153, 0xbfb8aa3b, v123
	v_exp_f32_e32 v153, v153
	s_nop 0
	v_add_f32_e32 v153, 1.0, v153
	v_rcp_f32_e32 v153, v153
	s_nop 0
	v_mul_f32_e32 v153, v123, v153
	ds_write_b32 v3, v153 offset:15360
	s_waitcnt vmcnt(19)
	v_mul_f32_e32 v152, 0xbfb8aa3b, v124
	v_exp_f32_e32 v152, v152
	s_nop 0
	v_add_f32_e32 v152, 1.0, v152
	v_rcp_f32_e32 v152, v152
	s_nop 0
	v_mul_f32_e32 v152, v124, v152
	ds_write_b32 v3, v152 offset:16384
	s_waitcnt vmcnt(18)
	v_mul_f32_e32 v153, 0xbfb8aa3b, v125
	v_exp_f32_e32 v153, v153
	s_nop 0
	v_add_f32_e32 v153, 1.0, v153
	v_rcp_f32_e32 v153, v153
	s_nop 0
	v_mul_f32_e32 v153, v125, v153
	ds_write_b32 v3, v153 offset:17408
	s_waitcnt vmcnt(17)
	v_mul_f32_e32 v152, 0xbfb8aa3b, v126
	v_exp_f32_e32 v152, v152
	s_nop 0
	v_add_f32_e32 v152, 1.0, v152
	v_rcp_f32_e32 v152, v152
	s_nop 0
	v_mul_f32_e32 v152, v126, v152
	ds_write_b32 v3, v152 offset:18432
	s_waitcnt vmcnt(16)
	v_mul_f32_e32 v153, 0xbfb8aa3b, v127
	v_exp_f32_e32 v153, v153
	s_nop 0
	v_add_f32_e32 v153, 1.0, v153
	v_rcp_f32_e32 v153, v153
	s_nop 0
	v_mul_f32_e32 v153, v127, v153
	ds_write_b32 v3, v153 offset:19456
	s_waitcnt vmcnt(15)
	v_mul_f32_e32 v152, 0xbfb8aa3b, v128
	v_exp_f32_e32 v152, v152
	s_nop 0
	v_add_f32_e32 v152, 1.0, v152
	v_rcp_f32_e32 v152, v152
	s_nop 0
	v_mul_f32_e32 v152, v128, v152
	ds_write_b32 v3, v152 offset:20480
	s_waitcnt vmcnt(14)
	v_mul_f32_e32 v153, 0xbfb8aa3b, v129
	v_exp_f32_e32 v153, v153
	s_nop 0
	v_add_f32_e32 v153, 1.0, v153
	v_rcp_f32_e32 v153, v153
	s_nop 0
	v_mul_f32_e32 v153, v129, v153
	ds_write_b32 v3, v153 offset:21504
	s_waitcnt vmcnt(13)
	v_mul_f32_e32 v152, 0xbfb8aa3b, v130
	v_exp_f32_e32 v152, v152
	s_nop 0
	v_add_f32_e32 v152, 1.0, v152
	v_rcp_f32_e32 v152, v152
	s_nop 0
	v_mul_f32_e32 v152, v130, v152
	ds_write_b32 v3, v152 offset:22528
	s_waitcnt vmcnt(12)
	v_mul_f32_e32 v153, 0xbfb8aa3b, v131
	v_exp_f32_e32 v153, v153
	s_nop 0
	v_add_f32_e32 v153, 1.0, v153
	v_rcp_f32_e32 v153, v153
	s_nop 0
	v_mul_f32_e32 v153, v131, v153
	ds_write_b32 v3, v153 offset:23552
	s_waitcnt vmcnt(11)
	v_mul_f32_e32 v152, 0xbfb8aa3b, v132
	v_exp_f32_e32 v152, v152
	s_nop 0
	v_add_f32_e32 v152, 1.0, v152
	v_rcp_f32_e32 v152, v152
	s_nop 0
	v_mul_f32_e32 v152, v132, v152
	ds_write_b32 v3, v152 offset:24576
	s_waitcnt vmcnt(10)
	v_mul_f32_e32 v153, 0xbfb8aa3b, v133
	v_exp_f32_e32 v153, v153
	s_nop 0
	v_add_f32_e32 v153, 1.0, v153
	v_rcp_f32_e32 v153, v153
	s_nop 0
	v_mul_f32_e32 v153, v133, v153
	ds_write_b32 v3, v153 offset:25600
	s_waitcnt vmcnt(9)
	v_mul_f32_e32 v152, 0xbfb8aa3b, v134
	v_exp_f32_e32 v152, v152
	s_nop 0
	v_add_f32_e32 v152, 1.0, v152
	v_rcp_f32_e32 v152, v152
	s_nop 0
	v_mul_f32_e32 v152, v134, v152
	ds_write_b32 v3, v152 offset:26624
	s_waitcnt vmcnt(8)
	v_mul_f32_e32 v153, 0xbfb8aa3b, v135
	v_exp_f32_e32 v153, v153
	s_nop 0
	v_add_f32_e32 v153, 1.0, v153
	v_rcp_f32_e32 v153, v153
	s_nop 0
	v_mul_f32_e32 v153, v135, v153
	ds_write_b32 v3, v153 offset:27648
	s_waitcnt vmcnt(7)
	v_mul_f32_e32 v152, 0xbfb8aa3b, v136
	v_exp_f32_e32 v152, v152
	s_nop 0
	v_add_f32_e32 v152, 1.0, v152
	v_rcp_f32_e32 v152, v152
	s_nop 0
	v_mul_f32_e32 v152, v136, v152
	ds_write_b32 v3, v152 offset:28672
	s_waitcnt vmcnt(6)
	v_mul_f32_e32 v153, 0xbfb8aa3b, v137
	v_exp_f32_e32 v153, v153
	s_nop 0
	v_add_f32_e32 v153, 1.0, v153
	v_rcp_f32_e32 v153, v153
	s_nop 0
	v_mul_f32_e32 v153, v137, v153
	ds_write_b32 v3, v153 offset:29696
	s_waitcnt vmcnt(5)
	v_mul_f32_e32 v152, 0xbfb8aa3b, v138
	v_exp_f32_e32 v152, v152
	s_nop 0
	v_add_f32_e32 v152, 1.0, v152
	v_rcp_f32_e32 v152, v152
	s_nop 0
	v_mul_f32_e32 v152, v138, v152
	ds_write_b32 v3, v152 offset:30720
	s_waitcnt vmcnt(4)
	v_mul_f32_e32 v153, 0xbfb8aa3b, v139
	v_exp_f32_e32 v153, v153
	s_nop 0
	v_add_f32_e32 v153, 1.0, v153
	v_rcp_f32_e32 v153, v153
	s_nop 0
	v_mul_f32_e32 v153, v139, v153
	ds_write_b32 v3, v153 offset:31744
	s_waitcnt vmcnt(3)
	v_mul_f32_e32 v152, 0xbfb8aa3b, v140
	v_exp_f32_e32 v152, v152
	s_nop 0
	v_add_f32_e32 v152, 1.0, v152
	v_rcp_f32_e32 v152, v152
	s_nop 0
	v_mul_f32_e32 v152, v140, v152
	ds_write_b32 v3, v152 offset:32768
	s_waitcnt vmcnt(2)
	v_mul_f32_e32 v153, 0xbfb8aa3b, v141
	v_exp_f32_e32 v153, v153
	s_nop 0
	v_add_f32_e32 v153, 1.0, v153
	v_rcp_f32_e32 v153, v153
	s_nop 0
	v_mul_f32_e32 v153, v141, v153
	ds_write_b32 v3, v153 offset:33792
	s_waitcnt vmcnt(1)
	v_mul_f32_e32 v152, 0xbfb8aa3b, v142
	v_exp_f32_e32 v152, v152
	s_nop 0
	v_add_f32_e32 v152, 1.0, v152
	v_rcp_f32_e32 v152, v152
	s_nop 0
	v_mul_f32_e32 v152, v142, v152
	ds_write_b32 v3, v152 offset:34816
	s_waitcnt vmcnt(0)
	v_mul_f32_e32 v153, 0xbfb8aa3b, v143
	v_exp_f32_e32 v153, v153
	s_nop 0
	v_add_f32_e32 v153, 1.0, v153
	v_rcp_f32_e32 v153, v153
	s_nop 0
	v_mul_f32_e32 v153, v143, v153
	ds_write_b32 v3, v153 offset:35840
	s_or_b64 exec, exec, s[28:29]
	v_ashrrev_i32_e32 v0, 8, v2
	v_add_u32_e32 v68, s63, v0
	v_mul_hi_i32 v0, v68, s43
	v_lshrrev_b32_e32 v1, 31, v0
	v_ashrrev_i32_e32 v0, 3, v0
	v_add_u32_e32 v48, v0, v1
	v_and_b32_e32 v70, 0x7c, v50
	v_lshrrev_b32_e32 v0, 5, v52
	v_lshl_or_b32 v2, v68, 7, v70
	v_mul_lo_u32 v51, v48, s45
	v_mul_hi_u32_u24_e32 v1, 0x300000, v0
	v_mul_u32_u24_e32 v0, 0x300000, v0
	v_sub_u32_e32 v2, v2, v51
	v_mad_i64_i32 v[0:1], s[28:29], v48, s44, v[0:1]
	v_ashrrev_i32_e32 v3, 31, v2
	v_lshrrev_b32_e32 v69, 5, v52
	v_lshl_add_u64 v[0:1], v[2:3], 2, v[0:1]
	v_mov_b32_e32 v32, 0
	v_lshl_add_u64 v[54:55], s[6:7], 0, v[0:1]
	v_lshl_add_u32 v71, v69, 9, v66
	s_mov_b64 s[28:29], 0
	v_mov_b32_e32 v33, v32
	v_mov_b32_e32 v34, v32
	v_mov_b32_e32 v35, v32
	v_mov_b32_e32 v28, v32
	v_mov_b32_e32 v29, v32
	v_mov_b32_e32 v30, v32
	v_mov_b32_e32 v31, v32
	v_mov_b32_e32 v24, v32
	v_mov_b32_e32 v25, v32
	v_mov_b32_e32 v26, v32
	v_mov_b32_e32 v27, v32
	v_mov_b32_e32 v20, v32
	v_mov_b32_e32 v21, v32
	v_mov_b32_e32 v22, v32
	v_mov_b32_e32 v23, v32
	v_mov_b32_e32 v16, v32
	v_mov_b32_e32 v17, v32
	v_mov_b32_e32 v18, v32
	v_mov_b32_e32 v19, v32
	v_mov_b32_e32 v12, v32
	v_mov_b32_e32 v13, v32
	v_mov_b32_e32 v14, v32
	v_mov_b32_e32 v15, v32
	v_mov_b32_e32 v8, v32
	v_mov_b32_e32 v9, v32
	v_mov_b32_e32 v10, v32
	v_mov_b32_e32 v11, v32
	v_mov_b32_e32 v4, v32
	v_mov_b32_e32 v5, v32
	v_mov_b32_e32 v6, v32
	v_mov_b32_e32 v7, v32
	v_mov_b32_e32 v0, v32
	v_mov_b32_e32 v1, v32
	v_mov_b32_e32 v2, v32
	v_mov_b32_e32 v3, v32
	s_waitcnt lgkmcnt(0)
	s_barrier
.LBB0_77:
	v_lshl_add_u64 v[56:57], v[54:55], 0, s[28:29]
	global_load_dwordx4 v[108:111], v[56:57], off
	v_add_co_u32_e32 v172, vcc, s46, v56
	s_nop 1
	v_addc_co_u32_e32 v173, vcc, 0, v57, vcc
	global_load_dwordx4 v[112:115], v[172:173], off
	v_add_co_u32_e32 v172, vcc, s47, v56
	s_nop 1
	v_addc_co_u32_e32 v173, vcc, 0, v57, vcc
	global_load_dwordx4 v[116:119], v[172:173], off
	v_add_co_u32_e32 v172, vcc, s48, v56
	s_nop 1
	v_addc_co_u32_e32 v173, vcc, 0, v57, vcc
	global_load_dwordx4 v[120:123], v[172:173], off
	v_add_co_u32_e32 v172, vcc, s49, v56
	s_nop 1
	v_addc_co_u32_e32 v173, vcc, 0, v57, vcc
	global_load_dwordx4 v[124:127], v[172:173], off
	v_add_co_u32_e32 v172, vcc, s50, v56
	s_nop 1
	v_addc_co_u32_e32 v173, vcc, 0, v57, vcc
	global_load_dwordx4 v[128:131], v[172:173], off
	v_add_co_u32_e32 v172, vcc, s51, v56
	s_nop 1
	v_addc_co_u32_e32 v173, vcc, 0, v57, vcc
	global_load_dwordx4 v[132:135], v[172:173], off
	v_add_co_u32_e32 v172, vcc, s52, v56
	s_nop 1
	v_addc_co_u32_e32 v173, vcc, 0, v57, vcc
	global_load_dwordx4 v[136:139], v[172:173], off
	v_add_co_u32_e32 v172, vcc, s53, v56
	s_nop 1
	v_addc_co_u32_e32 v173, vcc, 0, v57, vcc
	global_load_dwordx4 v[140:143], v[172:173], off
	v_add_co_u32_e32 v172, vcc, s54, v56
	s_nop 1
	v_addc_co_u32_e32 v173, vcc, 0, v57, vcc
	global_load_dwordx4 v[144:147], v[172:173], off
	v_add_co_u32_e32 v172, vcc, s55, v56
	s_nop 1
	v_addc_co_u32_e32 v173, vcc, 0, v57, vcc
	global_load_dwordx4 v[148:151], v[172:173], off
	v_add_co_u32_e32 v172, vcc, s56, v56
	s_nop 1
	v_addc_co_u32_e32 v173, vcc, 0, v57, vcc
	global_load_dwordx4 v[152:155], v[172:173], off
	v_add_co_u32_e32 v172, vcc, s57, v56
	s_nop 1
	v_addc_co_u32_e32 v173, vcc, 0, v57, vcc
	global_load_dwordx4 v[156:159], v[172:173], off
	v_add_co_u32_e32 v172, vcc, s58, v56
	s_nop 1
	v_addc_co_u32_e32 v173, vcc, 0, v57, vcc
	global_load_dwordx4 v[160:163], v[172:173], off
	v_add_co_u32_e32 v172, vcc, s59, v56
	s_nop 1
	v_addc_co_u32_e32 v173, vcc, 0, v57, vcc
	global_load_dwordx4 v[164:167], v[172:173], off
	v_add_co_u32_e32 v172, vcc, s60, v56
	s_nop 1
	v_addc_co_u32_e32 v173, vcc, 0, v57, vcc
	global_load_dwordx4 v[168:171], v[172:173], off
	ds_read_b128 v[58:61], v71
	ds_read_b128 v[44:47], v71 offset:16
	ds_read_b128 v[40:43], v71 offset:32
	ds_read_b128 v[36:39], v71 offset:48
	s_add_u32 s28, s28, 0x60000
	s_addc_u32 s29, s29, 0
	s_cmp_eq_u32 s28, 0x300000
	s_waitcnt vmcnt(15) lgkmcnt(3)
	v_pk_fma_f32 v[76:77], v[108:109], v[58:59], v[32:33] op_sel_hi:[1, 0, 1]
	v_pk_fma_f32 v[78:79], v[110:111], v[58:59], v[34:35] op_sel_hi:[1, 0, 1]
	ds_read_b128 v[32:35], v71 offset:4096
	s_waitcnt lgkmcnt(0)
	v_pk_fma_f32 v[80:81], v[108:109], v[32:33], v[28:29] op_sel_hi:[1, 0, 1]
	v_pk_fma_f32 v[82:83], v[110:111], v[32:33], v[30:31] op_sel_hi:[1, 0, 1]
	ds_read_b128 v[28:31], v71 offset:8192
	s_waitcnt lgkmcnt(0)
	v_pk_fma_f32 v[84:85], v[108:109], v[28:29], v[24:25] op_sel_hi:[1, 0, 1]
	v_pk_fma_f32 v[86:87], v[110:111], v[28:29], v[26:27] op_sel_hi:[1, 0, 1]
	ds_read_b128 v[24:27], v71 offset:12288
	s_waitcnt lgkmcnt(0)
	v_pk_fma_f32 v[88:89], v[108:109], v[24:25], v[20:21] op_sel_hi:[1, 0, 1]
	v_pk_fma_f32 v[90:91], v[110:111], v[24:25], v[22:23] op_sel_hi:[1, 0, 1]
	ds_read_b128 v[20:23], v71 offset:16384
	s_waitcnt lgkmcnt(0)
	v_pk_fma_f32 v[92:93], v[108:109], v[20:21], v[16:17] op_sel_hi:[1, 0, 1]
	v_pk_fma_f32 v[94:95], v[110:111], v[20:21], v[18:19] op_sel_hi:[1, 0, 1]
	ds_read_b128 v[16:19], v71 offset:20480
	s_waitcnt lgkmcnt(0)
	v_pk_fma_f32 v[96:97], v[108:109], v[16:17], v[12:13] op_sel_hi:[1, 0, 1]
	v_pk_fma_f32 v[98:99], v[110:111], v[16:17], v[14:15] op_sel_hi:[1, 0, 1]
	ds_read_b128 v[12:15], v71 offset:24576
	s_waitcnt lgkmcnt(0)
	v_pk_fma_f32 v[100:101], v[108:109], v[12:13], v[8:9] op_sel_hi:[1, 0, 1]
	v_pk_fma_f32 v[102:103], v[110:111], v[12:13], v[10:11] op_sel_hi:[1, 0, 1]
	ds_read_b128 v[8:11], v71 offset:28672
	s_waitcnt lgkmcnt(0)
	v_pk_fma_f32 v[104:105], v[108:109], v[8:9], v[4:5] op_sel_hi:[1, 0, 1]
	v_pk_fma_f32 v[106:107], v[110:111], v[8:9], v[6:7] op_sel_hi:[1, 0, 1]
	ds_read_b128 v[4:7], v71 offset:32768
	s_waitcnt lgkmcnt(0)
	v_pk_fma_f32 v[72:73], v[108:109], v[4:5], v[0:1] op_sel_hi:[1, 0, 1]
	v_pk_fma_f32 v[74:75], v[110:111], v[4:5], v[2:3] op_sel_hi:[1, 0, 1]
	s_nop 0
	s_waitcnt vmcnt(14)
	v_pk_fma_f32 v[76:77], v[112:113], v[58:59], v[76:77] op_sel:[0, 1, 0]
	v_pk_fma_f32 v[58:59], v[114:115], v[58:59], v[78:79] op_sel:[0, 1, 0]
	v_pk_fma_f32 v[78:79], v[112:113], v[32:33], v[80:81] op_sel:[0, 1, 0]
	v_pk_fma_f32 v[32:33], v[114:115], v[32:33], v[82:83] op_sel:[0, 1, 0]
	v_pk_fma_f32 v[80:81], v[112:113], v[28:29], v[84:85] op_sel:[0, 1, 0]
	v_pk_fma_f32 v[28:29], v[114:115], v[28:29], v[86:87] op_sel:[0, 1, 0]
	v_pk_fma_f32 v[82:83], v[112:113], v[24:25], v[88:89] op_sel:[0, 1, 0]
	v_pk_fma_f32 v[24:25], v[114:115], v[24:25], v[90:91] op_sel:[0, 1, 0]
	v_pk_fma_f32 v[84:85], v[112:113], v[20:21], v[92:93] op_sel:[0, 1, 0]
	v_pk_fma_f32 v[86:87], v[112:113], v[16:17], v[96:97] op_sel:[0, 1, 0]
	v_pk_fma_f32 v[88:89], v[112:113], v[12:13], v[100:101] op_sel:[0, 1, 0]
	v_pk_fma_f32 v[90:91], v[112:113], v[8:9], v[104:105] op_sel:[0, 1, 0]
	v_pk_fma_f32 v[72:73], v[112:113], v[4:5], v[72:73] op_sel:[0, 1, 0]
	v_pk_fma_f32 v[20:21], v[114:115], v[20:21], v[94:95] op_sel:[0, 1, 0]
	s_nop 0
	v_pk_fma_f32 v[16:17], v[114:115], v[16:17], v[98:99] op_sel:[0, 1, 0]
	v_pk_fma_f32 v[12:13], v[114:115], v[12:13], v[102:103] op_sel:[0, 1, 0]
	v_pk_fma_f32 v[8:9], v[114:115], v[8:9], v[106:107] op_sel:[0, 1, 0]
	v_pk_fma_f32 v[4:5], v[114:115], v[4:5], v[74:75] op_sel:[0, 1, 0]
	s_waitcnt vmcnt(13)
	v_pk_fma_f32 v[74:75], v[116:117], v[60:61], v[76:77] op_sel_hi:[1, 0, 1]
	v_pk_fma_f32 v[76:77], v[116:117], v[34:35], v[78:79] op_sel_hi:[1, 0, 1]
	v_pk_fma_f32 v[78:79], v[116:117], v[30:31], v[80:81] op_sel_hi:[1, 0, 1]
	v_pk_fma_f32 v[80:81], v[116:117], v[26:27], v[82:83] op_sel_hi:[1, 0, 1]
	v_pk_fma_f32 v[82:83], v[116:117], v[22:23], v[84:85] op_sel_hi:[1, 0, 1]
	v_pk_fma_f32 v[84:85], v[116:117], v[18:19], v[86:87] op_sel_hi:[1, 0, 1]
	v_pk_fma_f32 v[86:87], v[116:117], v[14:15], v[88:89] op_sel_hi:[1, 0, 1]
	v_pk_fma_f32 v[88:89], v[116:117], v[10:11], v[90:91] op_sel_hi:[1, 0, 1]
	v_pk_fma_f32 v[72:73], v[116:117], v[6:7], v[72:73] op_sel_hi:[1, 0, 1]
	v_pk_fma_f32 v[58:59], v[118:119], v[60:61], v[58:59] op_sel_hi:[1, 0, 1]
	s_nop 0
	v_pk_fma_f32 v[32:33], v[118:119], v[34:35], v[32:33] op_sel_hi:[1, 0, 1]
	v_pk_fma_f32 v[28:29], v[118:119], v[30:31], v[28:29] op_sel_hi:[1, 0, 1]
	v_pk_fma_f32 v[24:25], v[118:119], v[26:27], v[24:25] op_sel_hi:[1, 0, 1]
	v_pk_fma_f32 v[20:21], v[118:119], v[22:23], v[20:21] op_sel_hi:[1, 0, 1]
	v_pk_fma_f32 v[16:17], v[118:119], v[18:19], v[16:17] op_sel_hi:[1, 0, 1]
	v_pk_fma_f32 v[12:13], v[118:119], v[14:15], v[12:13] op_sel_hi:[1, 0, 1]
	v_pk_fma_f32 v[8:9], v[118:119], v[10:11], v[8:9] op_sel_hi:[1, 0, 1]
	v_pk_fma_f32 v[90:91], v[118:119], v[6:7], v[4:5] op_sel_hi:[1, 0, 1]
	v_mov_b32_e32 v4, v61
	v_mov_b32_e32 v6, v7
	s_waitcnt vmcnt(12)
	v_pk_fma_f32 v[74:75], v[120:121], v[4:5], v[74:75] op_sel_hi:[1, 0, 1]
	v_pk_fma_f32 v[92:93], v[122:123], v[4:5], v[58:59] op_sel_hi:[1, 0, 1]
	v_mov_b32_e32 v4, v35
	v_pk_fma_f32 v[58:59], v[120:121], v[4:5], v[76:77] op_sel_hi:[1, 0, 1]
	v_pk_fma_f32 v[60:61], v[122:123], v[4:5], v[32:33] op_sel_hi:[1, 0, 1]
	v_mov_b32_e32 v4, v31
	v_pk_fma_f32 v[32:33], v[120:121], v[4:5], v[78:79] op_sel_hi:[1, 0, 1]
	v_pk_fma_f32 v[34:35], v[122:123], v[4:5], v[28:29] op_sel_hi:[1, 0, 1]
	v_mov_b32_e32 v4, v27
	v_pk_fma_f32 v[28:29], v[120:121], v[4:5], v[80:81] op_sel_hi:[1, 0, 1]
	v_pk_fma_f32 v[30:31], v[122:123], v[4:5], v[24:25] op_sel_hi:[1, 0, 1]
	v_mov_b32_e32 v4, v23
	v_pk_fma_f32 v[24:25], v[120:121], v[4:5], v[82:83] op_sel_hi:[1, 0, 1]
	v_pk_fma_f32 v[26:27], v[122:123], v[4:5], v[20:21] op_sel_hi:[1, 0, 1]
	v_mov_b32_e32 v4, v19
	v_pk_fma_f32 v[20:21], v[120:121], v[4:5], v[84:85] op_sel_hi:[1, 0, 1]
	v_pk_fma_f32 v[22:23], v[122:123], v[4:5], v[16:17] op_sel_hi:[1, 0, 1]
	v_mov_b32_e32 v4, v15
	v_pk_fma_f32 v[16:17], v[120:121], v[4:5], v[86:87] op_sel_hi:[1, 0, 1]
	v_pk_fma_f32 v[18:19], v[122:123], v[4:5], v[12:13] op_sel_hi:[1, 0, 1]
	v_mov_b32_e32 v4, v11
	v_pk_fma_f32 v[12:13], v[120:121], v[4:5], v[88:89] op_sel_hi:[1, 0, 1]
	v_pk_fma_f32 v[14:15], v[122:123], v[4:5], v[8:9] op_sel_hi:[1, 0, 1]
	v_pk_fma_f32 v[4:5], v[120:121], v[6:7], v[72:73] op_sel_hi:[1, 0, 1]
	v_pk_fma_f32 v[6:7], v[122:123], v[6:7], v[90:91] op_sel_hi:[1, 0, 1]
	s_nop 0
	ds_read_b128 v[84:87], v71 offset:32784
	ds_read_b128 v[76:79], v71 offset:24592
	ds_read_b128 v[80:83], v71 offset:28688
	s_waitcnt vmcnt(11)
	v_pk_fma_f32 v[8:9], v[124:125], v[44:45], v[74:75] op_sel_hi:[1, 0, 1]
	ds_read_b128 v[72:75], v71 offset:4112
	v_pk_fma_f32 v[10:11], v[126:127], v[44:45], v[92:93] op_sel_hi:[1, 0, 1]
	s_waitcnt lgkmcnt(2)
	v_pk_fma_f32 v[16:17], v[124:125], v[76:77], v[16:17] op_sel_hi:[1, 0, 1]
	s_waitcnt lgkmcnt(1)
	v_pk_fma_f32 v[12:13], v[124:125], v[80:81], v[12:13] op_sel_hi:[1, 0, 1]
	v_pk_fma_f32 v[4:5], v[124:125], v[84:85], v[4:5] op_sel_hi:[1, 0, 1]
	s_waitcnt lgkmcnt(0)
	v_pk_fma_f32 v[88:89], v[124:125], v[72:73], v[58:59] op_sel_hi:[1, 0, 1]
	v_pk_fma_f32 v[90:91], v[126:127], v[72:73], v[60:61] op_sel_hi:[1, 0, 1]
	ds_read_b128 v[58:61], v71 offset:8208
	v_pk_fma_f32 v[18:19], v[126:127], v[76:77], v[18:19] op_sel_hi:[1, 0, 1]
	v_pk_fma_f32 v[14:15], v[126:127], v[80:81], v[14:15] op_sel_hi:[1, 0, 1]
	v_pk_fma_f32 v[6:7], v[126:127], v[84:85], v[6:7] op_sel_hi:[1, 0, 1]
	s_waitcnt lgkmcnt(0)
	v_pk_fma_f32 v[92:93], v[124:125], v[58:59], v[32:33] op_sel_hi:[1, 0, 1]
	v_pk_fma_f32 v[94:95], v[126:127], v[58:59], v[34:35] op_sel_hi:[1, 0, 1]
	ds_read_b128 v[32:35], v71 offset:12304
	s_waitcnt lgkmcnt(0)
	v_pk_fma_f32 v[96:97], v[124:125], v[32:33], v[28:29] op_sel_hi:[1, 0, 1]
	v_pk_fma_f32 v[98:99], v[126:127], v[32:33], v[30:31] op_sel_hi:[1, 0, 1]
	ds_read_b128 v[28:31], v71 offset:16400
	s_waitcnt lgkmcnt(0)
	v_pk_fma_f32 v[100:101], v[124:125], v[28:29], v[24:25] op_sel_hi:[1, 0, 1]
	v_pk_fma_f32 v[102:103], v[126:127], v[28:29], v[26:27] op_sel_hi:[1, 0, 1]
	ds_read_b128 v[24:27], v71 offset:20496
	s_waitcnt lgkmcnt(0)
	v_pk_fma_f32 v[20:21], v[124:125], v[24:25], v[20:21] op_sel_hi:[1, 0, 1]
	v_pk_fma_f32 v[22:23], v[126:127], v[24:25], v[22:23] op_sel_hi:[1, 0, 1]
	s_nop 0
	s_waitcnt vmcnt(10)
	v_pk_fma_f32 v[8:9], v[128:129], v[44:45], v[8:9] op_sel:[0, 1, 0]
	v_pk_fma_f32 v[10:11], v[130:131], v[44:45], v[10:11] op_sel:[0, 1, 0]
	v_pk_fma_f32 v[44:45], v[128:129], v[72:73], v[88:89] op_sel:[0, 1, 0]
	v_pk_fma_f32 v[72:73], v[130:131], v[72:73], v[90:91] op_sel:[0, 1, 0]
	v_pk_fma_f32 v[88:89], v[128:129], v[58:59], v[92:93] op_sel:[0, 1, 0]
	v_pk_fma_f32 v[90:91], v[128:129], v[32:33], v[96:97] op_sel:[0, 1, 0]
	v_pk_fma_f32 v[92:93], v[128:129], v[28:29], v[100:101] op_sel:[0, 1, 0]
	v_pk_fma_f32 v[20:21], v[128:129], v[24:25], v[20:21] op_sel:[0, 1, 0]
	v_pk_fma_f32 v[16:17], v[128:129], v[76:77], v[16:17] op_sel:[0, 1, 0]
	v_pk_fma_f32 v[12:13], v[128:129], v[80:81], v[12:13] op_sel:[0, 1, 0]
	v_pk_fma_f32 v[4:5], v[128:129], v[84:85], v[4:5] op_sel:[0, 1, 0]
	v_pk_fma_f32 v[58:59], v[130:131], v[58:59], v[94:95] op_sel:[0, 1, 0]
	s_nop 0
	v_pk_fma_f32 v[32:33], v[130:131], v[32:33], v[98:99] op_sel:[0, 1, 0]
	v_pk_fma_f32 v[28:29], v[130:131], v[28:29], v[102:103] op_sel:[0, 1, 0]
	v_pk_fma_f32 v[22:23], v[130:131], v[24:25], v[22:23] op_sel:[0, 1, 0]
	v_pk_fma_f32 v[18:19], v[130:131], v[76:77], v[18:19] op_sel:[0, 1, 0]
	v_pk_fma_f32 v[14:15], v[130:131], v[80:81], v[14:15] op_sel:[0, 1, 0]
	v_pk_fma_f32 v[6:7], v[130:131], v[84:85], v[6:7] op_sel:[0, 1, 0]
	s_waitcnt vmcnt(9)
	v_pk_fma_f32 v[8:9], v[132:133], v[46:47], v[8:9] op_sel_hi:[1, 0, 1]
	v_pk_fma_f32 v[24:25], v[132:133], v[74:75], v[44:45] op_sel_hi:[1, 0, 1]
	v_pk_fma_f32 v[44:45], v[134:135], v[74:75], v[72:73] op_sel_hi:[1, 0, 1]
	v_pk_fma_f32 v[72:73], v[132:133], v[60:61], v[88:89] op_sel_hi:[1, 0, 1]
	v_pk_fma_f32 v[76:77], v[132:133], v[34:35], v[90:91] op_sel_hi:[1, 0, 1]
	v_pk_fma_f32 v[80:81], v[132:133], v[30:31], v[92:93] op_sel_hi:[1, 0, 1]
	v_pk_fma_f32 v[20:21], v[132:133], v[26:27], v[20:21] op_sel_hi:[1, 0, 1]
	v_pk_fma_f32 v[84:85], v[132:133], v[78:79], v[16:17] op_sel_hi:[1, 0, 1]
	v_pk_fma_f32 v[90:91], v[132:133], v[82:83], v[12:13] op_sel_hi:[1, 0, 1]
	v_pk_fma_f32 v[94:95], v[132:133], v[86:87], v[4:5] op_sel_hi:[1, 0, 1]
	v_pk_fma_f32 v[10:11], v[134:135], v[46:47], v[10:11] op_sel_hi:[1, 0, 1]
	s_nop 0
	v_pk_fma_f32 v[58:59], v[134:135], v[60:61], v[58:59] op_sel_hi:[1, 0, 1]
	v_pk_fma_f32 v[32:33], v[134:135], v[34:35], v[32:33] op_sel_hi:[1, 0, 1]
	v_pk_fma_f32 v[28:29], v[134:135], v[30:31], v[28:29] op_sel_hi:[1, 0, 1]
	v_pk_fma_f32 v[22:23], v[134:135], v[26:27], v[22:23] op_sel_hi:[1, 0, 1]
	v_pk_fma_f32 v[88:89], v[134:135], v[78:79], v[18:19] op_sel_hi:[1, 0, 1]
	v_pk_fma_f32 v[92:93], v[134:135], v[82:83], v[14:15] op_sel_hi:[1, 0, 1]
	v_pk_fma_f32 v[96:97], v[134:135], v[86:87], v[6:7] op_sel_hi:[1, 0, 1]
	v_mov_b32_e32 v4, v47
	v_mov_b32_e32 v6, v75
	v_mov_b32_e32 v14, v35
	v_mov_b32_e32 v18, v31
	v_mov_b32_e32 v26, v79
	v_mov_b32_e32 v30, v83
	v_mov_b32_e32 v34, v87
	s_waitcnt vmcnt(8)
	v_pk_fma_f32 v[46:47], v[136:137], v[4:5], v[8:9] op_sel_hi:[1, 0, 1]
	v_pk_fma_f32 v[98:99], v[138:139], v[4:5], v[10:11] op_sel_hi:[1, 0, 1]
	v_pk_fma_f32 v[4:5], v[136:137], v[6:7], v[24:25] op_sel_hi:[1, 0, 1]
	v_mov_b32_e32 v10, v61
	v_mov_b32_e32 v24, v27
	v_pk_fma_f32 v[8:9], v[136:137], v[10:11], v[72:73] op_sel_hi:[1, 0, 1]
	v_pk_fma_f32 v[12:13], v[136:137], v[14:15], v[76:77] op_sel_hi:[1, 0, 1]
	v_pk_fma_f32 v[14:15], v[138:139], v[14:15], v[32:33] op_sel_hi:[1, 0, 1]
	v_pk_fma_f32 v[16:17], v[136:137], v[18:19], v[80:81] op_sel_hi:[1, 0, 1]
	v_pk_fma_f32 v[18:19], v[138:139], v[18:19], v[28:29] op_sel_hi:[1, 0, 1]
	v_pk_fma_f32 v[20:21], v[136:137], v[24:25], v[20:21] op_sel_hi:[1, 0, 1]
	v_pk_fma_f32 v[22:23], v[138:139], v[24:25], v[22:23] op_sel_hi:[1, 0, 1]
	v_pk_fma_f32 v[24:25], v[136:137], v[26:27], v[84:85] op_sel_hi:[1, 0, 1]
	v_pk_fma_f32 v[28:29], v[136:137], v[30:31], v[90:91] op_sel_hi:[1, 0, 1]
	v_pk_fma_f32 v[32:33], v[136:137], v[34:35], v[94:95] op_sel_hi:[1, 0, 1]
	v_pk_fma_f32 v[6:7], v[138:139], v[6:7], v[44:45] op_sel_hi:[1, 0, 1]
	s_nop 0
	v_pk_fma_f32 v[10:11], v[138:139], v[10:11], v[58:59] op_sel_hi:[1, 0, 1]
	v_pk_fma_f32 v[26:27], v[138:139], v[26:27], v[88:89] op_sel_hi:[1, 0, 1]
	v_pk_fma_f32 v[30:31], v[138:139], v[30:31], v[92:93] op_sel_hi:[1, 0, 1]
	v_pk_fma_f32 v[34:35], v[138:139], v[34:35], v[96:97] op_sel_hi:[1, 0, 1]
	ds_read_b128 v[58:61], v71 offset:4128
	ds_read_b128 v[80:83], v71 offset:32800
	ds_read_b128 v[72:75], v71 offset:24608
	ds_read_b128 v[76:79], v71 offset:28704
	s_waitcnt vmcnt(7) lgkmcnt(3)
	v_pk_fma_f32 v[84:85], v[140:141], v[58:59], v[4:5] op_sel_hi:[1, 0, 1]
	v_pk_fma_f32 v[86:87], v[142:143], v[58:59], v[6:7] op_sel_hi:[1, 0, 1]
	ds_read_b128 v[4:7], v71 offset:8224
	v_pk_fma_f32 v[44:45], v[140:141], v[40:41], v[46:47] op_sel_hi:[1, 0, 1]
	v_pk_fma_f32 v[46:47], v[142:143], v[40:41], v[98:99] op_sel_hi:[1, 0, 1]
	s_waitcnt lgkmcnt(2)
	v_pk_fma_f32 v[24:25], v[140:141], v[72:73], v[24:25] op_sel_hi:[1, 0, 1]
	s_waitcnt lgkmcnt(1)
	v_pk_fma_f32 v[28:29], v[140:141], v[76:77], v[28:29] op_sel_hi:[1, 0, 1]
	s_waitcnt lgkmcnt(0)
	v_pk_fma_f32 v[88:89], v[140:141], v[4:5], v[8:9] op_sel_hi:[1, 0, 1]
	v_pk_fma_f32 v[90:91], v[142:143], v[4:5], v[10:11] op_sel_hi:[1, 0, 1]
	ds_read_b128 v[8:11], v71 offset:12320
	v_pk_fma_f32 v[32:33], v[140:141], v[80:81], v[32:33] op_sel_hi:[1, 0, 1]
	v_pk_fma_f32 v[26:27], v[142:143], v[72:73], v[26:27] op_sel_hi:[1, 0, 1]
	v_pk_fma_f32 v[30:31], v[142:143], v[76:77], v[30:31] op_sel_hi:[1, 0, 1]
	v_pk_fma_f32 v[34:35], v[142:143], v[80:81], v[34:35] op_sel_hi:[1, 0, 1]
	s_waitcnt lgkmcnt(0)
	v_pk_fma_f32 v[92:93], v[140:141], v[8:9], v[12:13] op_sel_hi:[1, 0, 1]
	v_pk_fma_f32 v[94:95], v[142:143], v[8:9], v[14:15] op_sel_hi:[1, 0, 1]
	ds_read_b128 v[12:15], v71 offset:16416
	s_waitcnt lgkmcnt(0)
	v_pk_fma_f32 v[96:97], v[140:141], v[12:13], v[16:17] op_sel_hi:[1, 0, 1]
	v_pk_fma_f32 v[98:99], v[142:143], v[12:13], v[18:19] op_sel_hi:[1, 0, 1]
	ds_read_b128 v[16:19], v71 offset:20512
	s_waitcnt lgkmcnt(0)
	v_pk_fma_f32 v[20:21], v[140:141], v[16:17], v[20:21] op_sel_hi:[1, 0, 1]
	v_pk_fma_f32 v[22:23], v[142:143], v[16:17], v[22:23] op_sel_hi:[1, 0, 1]
	s_nop 0
	s_waitcnt vmcnt(6)
	v_pk_fma_f32 v[44:45], v[144:145], v[40:41], v[44:45] op_sel:[0, 1, 0]
	v_pk_fma_f32 v[40:41], v[146:147], v[40:41], v[46:47] op_sel:[0, 1, 0]
	v_pk_fma_f32 v[46:47], v[144:145], v[58:59], v[84:85] op_sel:[0, 1, 0]
	v_pk_fma_f32 v[58:59], v[146:147], v[58:59], v[86:87] op_sel:[0, 1, 0]
	v_pk_fma_f32 v[84:85], v[144:145], v[4:5], v[88:89] op_sel:[0, 1, 0]
	v_pk_fma_f32 v[86:87], v[144:145], v[8:9], v[92:93] op_sel:[0, 1, 0]
	v_pk_fma_f32 v[88:89], v[144:145], v[12:13], v[96:97] op_sel:[0, 1, 0]
	v_pk_fma_f32 v[20:21], v[144:145], v[16:17], v[20:21] op_sel:[0, 1, 0]
	v_pk_fma_f32 v[16:17], v[146:147], v[16:17], v[22:23] op_sel:[0, 1, 0]
	v_pk_fma_f32 v[22:23], v[144:145], v[72:73], v[24:25] op_sel:[0, 1, 0]
	v_pk_fma_f32 v[24:25], v[146:147], v[72:73], v[26:27] op_sel:[0, 1, 0]
	v_pk_fma_f32 v[26:27], v[144:145], v[76:77], v[28:29] op_sel:[0, 1, 0]
	v_pk_fma_f32 v[28:29], v[146:147], v[76:77], v[30:31] op_sel:[0, 1, 0]
	v_pk_fma_f32 v[30:31], v[144:145], v[80:81], v[32:33] op_sel:[0, 1, 0]
	v_pk_fma_f32 v[4:5], v[146:147], v[4:5], v[90:91] op_sel:[0, 1, 0]
	s_nop 0
	v_pk_fma_f32 v[8:9], v[146:147], v[8:9], v[94:95] op_sel:[0, 1, 0]
	v_pk_fma_f32 v[12:13], v[146:147], v[12:13], v[98:99] op_sel:[0, 1, 0]
	v_pk_fma_f32 v[32:33], v[146:147], v[80:81], v[34:35] op_sel:[0, 1, 0]
	s_waitcnt vmcnt(5)
	v_pk_fma_f32 v[34:35], v[148:149], v[42:43], v[44:45] op_sel_hi:[1, 0, 1]
	v_pk_fma_f32 v[44:45], v[148:149], v[60:61], v[46:47] op_sel_hi:[1, 0, 1]
	v_pk_fma_f32 v[46:47], v[150:151], v[60:61], v[58:59] op_sel_hi:[1, 0, 1]
	v_pk_fma_f32 v[58:59], v[148:149], v[6:7], v[84:85] op_sel_hi:[1, 0, 1]
	v_pk_fma_f32 v[72:73], v[148:149], v[10:11], v[86:87] op_sel_hi:[1, 0, 1]
	v_pk_fma_f32 v[76:77], v[148:149], v[14:15], v[88:89] op_sel_hi:[1, 0, 1]
	v_pk_fma_f32 v[20:21], v[148:149], v[18:19], v[20:21] op_sel_hi:[1, 0, 1]
	v_pk_fma_f32 v[80:81], v[148:149], v[74:75], v[22:23] op_sel_hi:[1, 0, 1]
	v_pk_fma_f32 v[86:87], v[148:149], v[78:79], v[26:27] op_sel_hi:[1, 0, 1]
	v_pk_fma_f32 v[90:91], v[148:149], v[82:83], v[30:31] op_sel_hi:[1, 0, 1]
	v_pk_fma_f32 v[40:41], v[150:151], v[42:43], v[40:41] op_sel_hi:[1, 0, 1]
	s_nop 0
	v_pk_fma_f32 v[4:5], v[150:151], v[6:7], v[4:5] op_sel_hi:[1, 0, 1]
	v_pk_fma_f32 v[8:9], v[150:151], v[10:11], v[8:9] op_sel_hi:[1, 0, 1]
	v_pk_fma_f32 v[12:13], v[150:151], v[14:15], v[12:13] op_sel_hi:[1, 0, 1]
	v_pk_fma_f32 v[16:17], v[150:151], v[18:19], v[16:17] op_sel_hi:[1, 0, 1]
	v_pk_fma_f32 v[84:85], v[150:151], v[74:75], v[24:25] op_sel_hi:[1, 0, 1]
	v_pk_fma_f32 v[88:89], v[150:151], v[78:79], v[28:29] op_sel_hi:[1, 0, 1]
	v_pk_fma_f32 v[92:93], v[150:151], v[82:83], v[32:33] op_sel_hi:[1, 0, 1]
	v_mov_b32_e32 v6, v43
	s_waitcnt vmcnt(4)
	v_pk_fma_f32 v[94:95], v[152:153], v[6:7], v[34:35] op_sel_hi:[1, 0, 1]
	v_pk_fma_f32 v[96:97], v[154:155], v[6:7], v[40:41] op_sel_hi:[1, 0, 1]
	v_mov_b32_e32 v6, v61
	v_pk_fma_f32 v[40:41], v[152:153], v[6:7], v[44:45] op_sel_hi:[1, 0, 1]
	v_pk_fma_f32 v[42:43], v[154:155], v[6:7], v[46:47] op_sel_hi:[1, 0, 1]
	v_mov_b32_e32 v6, v7
	v_pk_fma_f32 v[34:35], v[154:155], v[6:7], v[4:5] op_sel_hi:[1, 0, 1]
	v_mov_b32_e32 v4, v11
	v_pk_fma_f32 v[28:29], v[152:153], v[4:5], v[72:73] op_sel_hi:[1, 0, 1]
	v_pk_fma_f32 v[30:31], v[154:155], v[4:5], v[8:9] op_sel_hi:[1, 0, 1]
	v_mov_b32_e32 v4, v15
	v_pk_fma_f32 v[24:25], v[152:153], v[4:5], v[76:77] op_sel_hi:[1, 0, 1]
	v_pk_fma_f32 v[26:27], v[154:155], v[4:5], v[12:13] op_sel_hi:[1, 0, 1]
	v_mov_b32_e32 v4, v19
	v_pk_fma_f32 v[20:21], v[152:153], v[4:5], v[20:21] op_sel_hi:[1, 0, 1]
	v_pk_fma_f32 v[22:23], v[154:155], v[4:5], v[16:17] op_sel_hi:[1, 0, 1]
	v_mov_b32_e32 v4, v75
	v_pk_fma_f32 v[32:33], v[152:153], v[6:7], v[58:59] op_sel_hi:[1, 0, 1]
	v_pk_fma_f32 v[16:17], v[152:153], v[4:5], v[80:81] op_sel_hi:[1, 0, 1]
	v_pk_fma_f32 v[18:19], v[154:155], v[4:5], v[84:85] op_sel_hi:[1, 0, 1]
	v_mov_b32_e32 v4, v79
	v_mov_b32_e32 v6, v83
	v_pk_fma_f32 v[12:13], v[152:153], v[4:5], v[86:87] op_sel_hi:[1, 0, 1]
	v_pk_fma_f32 v[14:15], v[154:155], v[4:5], v[88:89] op_sel_hi:[1, 0, 1]
	v_pk_fma_f32 v[4:5], v[152:153], v[6:7], v[90:91] op_sel_hi:[1, 0, 1]
	v_pk_fma_f32 v[6:7], v[154:155], v[6:7], v[92:93] op_sel_hi:[1, 0, 1]
	s_nop 0
	ds_read_b128 v[44:47], v71 offset:4144
	ds_read_b128 v[88:91], v71 offset:32816
	ds_read_b128 v[58:61], v71 offset:12336
	ds_read_b128 v[72:75], v71 offset:16432
	ds_read_b128 v[76:79], v71 offset:20528
	ds_read_b128 v[80:83], v71 offset:24624
	ds_read_b128 v[84:87], v71 offset:28720
	s_waitcnt vmcnt(3)
	v_pk_fma_f32 v[8:9], v[156:157], v[36:37], v[94:95] op_sel_hi:[1, 0, 1]
	s_waitcnt lgkmcnt(6)
	v_pk_fma_f32 v[92:93], v[156:157], v[44:45], v[40:41] op_sel_hi:[1, 0, 1]
	v_pk_fma_f32 v[94:95], v[158:159], v[44:45], v[42:43] op_sel_hi:[1, 0, 1]
	ds_read_b128 v[40:43], v71 offset:8240
	s_waitcnt lgkmcnt(5)
	v_pk_fma_f32 v[28:29], v[156:157], v[58:59], v[28:29] op_sel_hi:[1, 0, 1]
	s_waitcnt lgkmcnt(4)
	v_pk_fma_f32 v[24:25], v[156:157], v[72:73], v[24:25] op_sel_hi:[1, 0, 1]
	s_waitcnt lgkmcnt(3)
	v_pk_fma_f32 v[20:21], v[156:157], v[76:77], v[20:21] op_sel_hi:[1, 0, 1]
	s_waitcnt lgkmcnt(2)
	v_pk_fma_f32 v[16:17], v[156:157], v[80:81], v[16:17] op_sel_hi:[1, 0, 1]
	s_waitcnt lgkmcnt(0)
	v_pk_fma_f32 v[32:33], v[156:157], v[40:41], v[32:33] op_sel_hi:[1, 0, 1]
	v_pk_fma_f32 v[12:13], v[156:157], v[84:85], v[12:13] op_sel_hi:[1, 0, 1]
	v_pk_fma_f32 v[4:5], v[156:157], v[88:89], v[4:5] op_sel_hi:[1, 0, 1]
	v_pk_fma_f32 v[10:11], v[158:159], v[36:37], v[96:97] op_sel_hi:[1, 0, 1]
	s_nop 0
	v_pk_fma_f32 v[34:35], v[158:159], v[40:41], v[34:35] op_sel_hi:[1, 0, 1]
	v_pk_fma_f32 v[30:31], v[158:159], v[58:59], v[30:31] op_sel_hi:[1, 0, 1]
	v_pk_fma_f32 v[26:27], v[158:159], v[72:73], v[26:27] op_sel_hi:[1, 0, 1]
	v_pk_fma_f32 v[22:23], v[158:159], v[76:77], v[22:23] op_sel_hi:[1, 0, 1]
	v_pk_fma_f32 v[18:19], v[158:159], v[80:81], v[18:19] op_sel_hi:[1, 0, 1]
	v_pk_fma_f32 v[14:15], v[158:159], v[84:85], v[14:15] op_sel_hi:[1, 0, 1]
	v_pk_fma_f32 v[6:7], v[158:159], v[88:89], v[6:7] op_sel_hi:[1, 0, 1]
	v_add_u32_e32 v71, 64, v71
	s_waitcnt vmcnt(2)
	v_pk_fma_f32 v[8:9], v[160:161], v[36:37], v[8:9] op_sel:[0, 1, 0]
	v_pk_fma_f32 v[10:11], v[162:163], v[36:37], v[10:11] op_sel:[0, 1, 0]
	v_pk_fma_f32 v[36:37], v[160:161], v[44:45], v[92:93] op_sel:[0, 1, 0]
	v_pk_fma_f32 v[32:33], v[160:161], v[40:41], v[32:33] op_sel:[0, 1, 0]
	v_pk_fma_f32 v[28:29], v[160:161], v[58:59], v[28:29] op_sel:[0, 1, 0]
	v_pk_fma_f32 v[24:25], v[160:161], v[72:73], v[24:25] op_sel:[0, 1, 0]
	v_pk_fma_f32 v[20:21], v[160:161], v[76:77], v[20:21] op_sel:[0, 1, 0]
	v_pk_fma_f32 v[16:17], v[160:161], v[80:81], v[16:17] op_sel:[0, 1, 0]
	v_pk_fma_f32 v[12:13], v[160:161], v[84:85], v[12:13] op_sel:[0, 1, 0]
	v_pk_fma_f32 v[4:5], v[160:161], v[88:89], v[4:5] op_sel:[0, 1, 0]
	v_pk_fma_f32 v[44:45], v[162:163], v[44:45], v[94:95] op_sel:[0, 1, 0]
	s_nop 0
	v_pk_fma_f32 v[34:35], v[162:163], v[40:41], v[34:35] op_sel:[0, 1, 0]
	v_pk_fma_f32 v[30:31], v[162:163], v[58:59], v[30:31] op_sel:[0, 1, 0]
	v_pk_fma_f32 v[26:27], v[162:163], v[72:73], v[26:27] op_sel:[0, 1, 0]
	v_pk_fma_f32 v[22:23], v[162:163], v[76:77], v[22:23] op_sel:[0, 1, 0]
	v_pk_fma_f32 v[18:19], v[162:163], v[80:81], v[18:19] op_sel:[0, 1, 0]
	v_pk_fma_f32 v[14:15], v[162:163], v[84:85], v[14:15] op_sel:[0, 1, 0]
	v_pk_fma_f32 v[6:7], v[162:163], v[88:89], v[6:7] op_sel:[0, 1, 0]
	s_waitcnt vmcnt(1)
	v_pk_fma_f32 v[8:9], v[164:165], v[38:39], v[8:9] op_sel_hi:[1, 0, 1]
	v_pk_fma_f32 v[36:37], v[164:165], v[46:47], v[36:37] op_sel_hi:[1, 0, 1]
	v_pk_fma_f32 v[40:41], v[166:167], v[46:47], v[44:45] op_sel_hi:[1, 0, 1]
	v_pk_fma_f32 v[44:45], v[164:165], v[42:43], v[32:33] op_sel_hi:[1, 0, 1]
	v_pk_fma_f32 v[72:73], v[164:165], v[60:61], v[28:29] op_sel_hi:[1, 0, 1]
	v_pk_fma_f32 v[80:81], v[164:165], v[74:75], v[24:25] op_sel_hi:[1, 0, 1]
	v_pk_fma_f32 v[88:89], v[164:165], v[78:79], v[20:21] op_sel_hi:[1, 0, 1]
	v_pk_fma_f32 v[94:95], v[164:165], v[82:83], v[16:17] op_sel_hi:[1, 0, 1]
	v_pk_fma_f32 v[98:99], v[164:165], v[86:87], v[12:13] op_sel_hi:[1, 0, 1]
	v_pk_fma_f32 v[102:103], v[164:165], v[90:91], v[4:5] op_sel_hi:[1, 0, 1]
	v_pk_fma_f32 v[10:11], v[166:167], v[38:39], v[10:11] op_sel_hi:[1, 0, 1]
	s_nop 0
	v_pk_fma_f32 v[58:59], v[166:167], v[42:43], v[34:35] op_sel_hi:[1, 0, 1]
	v_pk_fma_f32 v[76:77], v[166:167], v[60:61], v[30:31] op_sel_hi:[1, 0, 1]
	v_pk_fma_f32 v[84:85], v[166:167], v[74:75], v[26:27] op_sel_hi:[1, 0, 1]
	v_pk_fma_f32 v[92:93], v[166:167], v[78:79], v[22:23] op_sel_hi:[1, 0, 1]
	v_pk_fma_f32 v[96:97], v[166:167], v[82:83], v[18:19] op_sel_hi:[1, 0, 1]
	v_pk_fma_f32 v[100:101], v[166:167], v[86:87], v[14:15] op_sel_hi:[1, 0, 1]
	v_pk_fma_f32 v[104:105], v[166:167], v[90:91], v[6:7] op_sel_hi:[1, 0, 1]
	v_mov_b32_e32 v4, v39
	v_mov_b32_e32 v6, v87
	s_waitcnt vmcnt(0)
	v_pk_fma_f32 v[32:33], v[168:169], v[4:5], v[8:9] op_sel_hi:[1, 0, 1]
	v_pk_fma_f32 v[34:35], v[170:171], v[4:5], v[10:11] op_sel_hi:[1, 0, 1]
	v_mov_b32_e32 v4, v47
	v_pk_fma_f32 v[28:29], v[168:169], v[4:5], v[36:37] op_sel_hi:[1, 0, 1]
	v_pk_fma_f32 v[30:31], v[170:171], v[4:5], v[40:41] op_sel_hi:[1, 0, 1]
	v_mov_b32_e32 v4, v43
	v_pk_fma_f32 v[24:25], v[168:169], v[4:5], v[44:45] op_sel_hi:[1, 0, 1]
	v_pk_fma_f32 v[26:27], v[170:171], v[4:5], v[58:59] op_sel_hi:[1, 0, 1]
	v_mov_b32_e32 v4, v61
	v_pk_fma_f32 v[20:21], v[168:169], v[4:5], v[72:73] op_sel_hi:[1, 0, 1]
	v_pk_fma_f32 v[22:23], v[170:171], v[4:5], v[76:77] op_sel_hi:[1, 0, 1]
	v_mov_b32_e32 v4, v75
	v_pk_fma_f32 v[16:17], v[168:169], v[4:5], v[80:81] op_sel_hi:[1, 0, 1]
	v_pk_fma_f32 v[18:19], v[170:171], v[4:5], v[84:85] op_sel_hi:[1, 0, 1]
	v_mov_b32_e32 v4, v79
	v_pk_fma_f32 v[12:13], v[168:169], v[4:5], v[88:89] op_sel_hi:[1, 0, 1]
	v_pk_fma_f32 v[14:15], v[170:171], v[4:5], v[92:93] op_sel_hi:[1, 0, 1]
	v_mov_b32_e32 v4, v83
	v_mov_b32_e32 v36, v91
	v_pk_fma_f32 v[8:9], v[168:169], v[4:5], v[94:95] op_sel_hi:[1, 0, 1]
	v_pk_fma_f32 v[10:11], v[170:171], v[4:5], v[96:97] op_sel_hi:[1, 0, 1]
	v_pk_fma_f32 v[4:5], v[168:169], v[6:7], v[98:99] op_sel_hi:[1, 0, 1]
	v_pk_fma_f32 v[6:7], v[170:171], v[6:7], v[100:101] op_sel_hi:[1, 0, 1]
	v_pk_fma_f32 v[0:1], v[168:169], v[36:37], v[102:103] op_sel_hi:[1, 0, 1]
	v_pk_fma_f32 v[2:3], v[170:171], v[36:37], v[104:105] op_sel_hi:[1, 0, 1]
	s_cbranch_scc0 .LBB0_77
	v_lshlrev_b32_e32 v37, 2, v70
	v_mul_u32_u24_e32 v38, 0x1200, v69
	v_mul_lo_u32 v36, v48, 48
	v_add3_u32 v37, v66, v37, v38
	v_sub_u32_e32 v36, v68, v36
	s_barrier
	ds_write_b128 v37, v[32:35]
	ds_write_b128 v37, v[28:31] offset:512
	ds_write_b128 v37, v[24:27] offset:1024
	ds_write_b128 v37, v[20:23] offset:1536
	ds_write_b128 v37, v[16:19] offset:2048
	ds_write_b128 v37, v[12:15] offset:2560
	ds_write_b128 v37, v[8:11] offset:3072
	ds_write_b128 v37, v[4:7] offset:3584
	ds_write_b128 v37, v[0:3] offset:4096
	v_lshrrev_b32_e32 v2, 7, v52
	v_lshlrev_b32_e32 v36, 7, v36
	v_mul_hi_u32_u24_e32 v3, 0x6000, v2
	v_mul_u32_u24_e32 v2, 0x6000, v2
	v_add_u32_e32 v0, v51, v36
	v_ashrrev_i32_e32 v37, 31, v36
	v_and_b32_e32 v5, 0x7f, v67
	v_mad_i64_i32 v[2:3], s[28:29], v48, s54, v[2:3]
	v_or_b32_e32 v0, v0, v5
	v_lshl_add_u64 v[2:3], v[36:37], 2, v[2:3]
	v_lshlrev_b32_e32 v5, 2, v5
	v_ashrrev_i32_e32 v1, 31, v0
	v_or_b32_e32 v2, v2, v5
	v_and_b32_e32 v6, 0x200, v50
	v_lshl_add_u64 v[0:1], v[0:1], 2, s[14:15]
	v_or_b32_e32 v4, 0xffffff00, v52
	v_lshl_add_u64 v[2:3], s[22:23], 0, v[2:3]
	v_add3_u32 v5, v66, v6, v5
	s_mov_b64 s[28:29], 0
	s_waitcnt lgkmcnt(0)
	s_barrier

.LBB0_1168:
	s_mov_b32 s98, s72
	s_cmpk_lg_i32 s33, 0x100
	s_cbranch_scc1 .Lctx_map_done
	s_and_b32 s98, s72, 7
	s_cmp_lt_u32 s98, 4
	s_cbranch_scc1 .LBB0_1801
	s_sub_u32 s98, s98, 4
	s_lshl_b32 s98, s98, 5
	s_lshr_b32 s99, s72, 3
	s_add_u32 s98, s98, s99
.Lctx_map_done:
	s_cmpk_gt_i32 s98, 0x67
	s_cbranch_scc1 .LBB0_1801
	s_add_i32 s38, s98, 0x980
	s_add_u32 s39, s20, 0x6400000
	s_addc_u32 s40, s21, 0
	s_add_u32 s22, s20, 0x1c00000
	s_addc_u32 s23, s21, 0
	s_add_u32 s24, s20, 0x1ec00000
	s_addc_u32 s25, s21, 0
	s_add_u32 s41, s20, 0x6400080
	s_addc_u32 s42, s21, 0
	v_mov_b32_e32 v129, 0
	s_movk_i32 s43, 0x6000
	s_movk_i32 s46, 0xc000
	s_movk_i32 s47, 0x7ff
	s_movk_i32 s48, 0x9ff
	s_movk_i32 s49, 0x11ff
	s_movk_i32 s50, 0x1220
	s_branch .LBB0_1172
